# attention: packed fp32 VOP3P ops split into single fp32 ops (7.5 packed-vs-scalar lever)
# speedup vs baseline: 1.0066x; 1.0066x over previous
.Lattn_nodma_A:
	v_lshl_add_u64 v[204:205], v[204:205], 0, s[76:77]
	v_lshl_add_u64 v[206:207], v[206:207], 0, s[76:77]
	v_lshl_add_u64 v[208:209], v[208:209], 0, s[28:29]
	v_lshl_add_u64 v[210:211], v[210:211], 0, s[52:53]
	v_lshl_add_u64 v[212:213], v[212:213], 0, s[52:53]
	s_waitcnt lgkmcnt(4)
	v_mfma_f32_32x32x16_bf16 v[80:95], v[2:5], v[156:159], 0
	v_mfma_f32_32x32x16_bf16 v[96:111], v[6:9], v[156:159], 0
	v_xor_b32_e32 v10, 0x60, v0
	ds_read_b128 v[2:5], v10
	ds_read_b128 v[6:9], v10 offset:8192
	s_waitcnt lgkmcnt(4)
	v_mfma_f32_32x32x16_bf16 v[80:95], v[244:247], v[152:155], v[80:95]
	v_mfma_f32_32x32x16_bf16 v[96:111], v[248:251], v[152:155], v[96:111]
	v_xor_b32_e32 v10, 0x80, v0
	ds_read_b128 v[244:247], v10
	ds_read_b128 v[248:251], v10 offset:8192
	s_waitcnt lgkmcnt(4)
	v_mfma_f32_32x32x16_bf16 v[80:95], v[12:15], v[148:151], v[80:95]
	v_mfma_f32_32x32x16_bf16 v[96:111], v[224:227], v[148:151], v[96:111]
	v_xor_b32_e32 v10, 0xa0, v0
	ds_read_b128 v[12:15], v10
	ds_read_b128 v[224:227], v10 offset:8192
	s_waitcnt lgkmcnt(4)
	v_mfma_f32_32x32x16_bf16 v[80:95], v[2:5], v[144:147], v[80:95]
	v_mfma_f32_32x32x16_bf16 v[96:111], v[6:9], v[144:147], v[96:111]
	v_xor_b32_e32 v10, 0xc0, v0
	ds_read_b128 v[2:5], v10
	ds_read_b128 v[6:9], v10 offset:8192
	s_waitcnt lgkmcnt(4)
	v_mfma_f32_32x32x16_bf16 v[80:95], v[244:247], v[140:143], v[80:95]
	v_mfma_f32_32x32x16_bf16 v[96:111], v[248:251], v[140:143], v[96:111]
	v_xor_b32_e32 v10, 0xe0, v0
	ds_read_b128 v[244:247], v10
	ds_read_b128 v[248:251], v10 offset:8192
	s_waitcnt lgkmcnt(4)
	v_mfma_f32_32x32x16_bf16 v[80:95], v[12:15], v[136:139], v[80:95]
	v_mfma_f32_32x32x16_bf16 v[96:111], v[224:227], v[136:139], v[96:111]
	v_add_u32_e32 v10, s18, v215
	ds_read_b128 v[12:15], v10 offset:16384
	ds_read_b128 v[224:227], v10 offset:20480
	s_waitcnt lgkmcnt(4)
	v_mfma_f32_32x32x16_bf16 v[80:95], v[2:5], v[132:135], v[80:95]
	v_mfma_f32_32x32x16_bf16 v[96:111], v[6:9], v[132:135], v[96:111]
	v_add_u32_e32 v11, s18, v216
	v_xad_u32 v10, v11, 32, 0
	ds_read_b128 v[2:5], v10
	ds_read_b128 v[6:9], v10 offset:4096
	s_waitcnt lgkmcnt(4)
	v_mfma_f32_32x32x16_bf16 v[80:95], v[244:247], v[128:131], v[80:95]
	v_mfma_f32_32x32x16_bf16 v[96:111], v[248:251], v[128:131], v[96:111]
	v_xad_u32 v10, v11, 64, 0
	ds_read_b128 v[244:247], v10
	ds_read_b128 v[248:251], v10 offset:4096
	s_waitcnt lgkmcnt(4)
	v_mfma_f32_32x32x16_bf16 v[80:95], v[12:15], v[124:127], v[80:95]
	v_mfma_f32_32x32x16_bf16 v[96:111], v[224:227], v[124:127], v[96:111]
	v_xor_b32_e32 v10, 0x60, v11
	ds_read_b128 v[12:15], v10
	ds_read_b128 v[224:227], v10 offset:4096
	s_waitcnt lgkmcnt(4)
	v_mfma_f32_32x32x16_bf16 v[80:95], v[2:5], v[120:123], v[80:95]
	v_mfma_f32_32x32x16_bf16 v[96:111], v[6:9], v[120:123], v[96:111]
	v_add_u32_e32 v228, s18, v217
	s_waitcnt lgkmcnt(2)
	v_mfma_f32_32x32x16_bf16 v[80:95], v[244:247], v[116:119], v[80:95]
	v_mfma_f32_32x32x16_bf16 v[96:111], v[248:251], v[116:119], v[96:111]
	ds_read_b128 v[244:247], v228 offset:24576
	ds_read_b128 v[248:251], v228 offset:28672
	s_waitcnt lgkmcnt(2)
	v_mfma_f32_32x32x16_bf16 v[80:95], v[12:15], v[112:115], v[80:95]
	v_mfma_f32_32x32x16_bf16 v[96:111], v[224:227], v[112:115], v[96:111]
	v_add_u32_e32 v229, s18, v218
	v_xad_u32 v243, v229, 32, 0
	v_xad_u32 v252, v229, 64, 0
	v_xor_b32_e32 v253, 0x60, v229
	s_nop 7
	s_nop 0
	v_max_f32_e32 v0, v81, v81
	v_max_f32_e32 v2, v80, v80
	v_max_f32_e32 v0, v2, v0
	v_max3_f32 v0, v0, v82, v83
	v_max3_f32 v0, v0, v84, v85
	v_max3_f32 v0, v0, v86, v87
	v_max3_f32 v0, v0, v88, v89
	v_max3_f32 v0, v0, v90, v91
	v_max3_f32 v0, v0, v92, v93
	v_max3_f32 v0, v0, v94, v95
	v_max3_f32 v0, v0, v96, v97
	v_max3_f32 v0, v0, v98, v99
	v_max3_f32 v0, v0, v100, v101
	v_max3_f32 v0, v0, v102, v103
	v_max3_f32 v0, v0, v104, v105
	v_max3_f32 v0, v0, v106, v107
	v_max3_f32 v0, v0, v108, v109
	v_max3_f32 v0, v0, v110, v111
	ds_bpermute_b32 v2, v219, v0
	s_waitcnt lgkmcnt(0)
	v_max3_f32 v2, v221, v0, v2
	v_sub_f32_e32 v0, v221, v2
	v_exp_f32_e32 v0, v0
	v_cmp_gt_f32_e32 vcc, v2, v221
	s_cbranch_vccz .Lattn_noscale_A
	v_mul_f32_e32 v78, v0, v78
	v_mul_f32_e32 v79, v0, v79
	v_mul_f32_e32 v76, v0, v76
	v_mul_f32_e32 v77, v0, v77
	v_mul_f32_e32 v74, v0, v74
	v_mul_f32_e32 v75, v0, v75
	v_mul_f32_e32 v72, v0, v72
	v_mul_f32_e32 v73, v0, v73
	v_mul_f32_e32 v70, v0, v70
	v_mul_f32_e32 v71, v0, v71
	v_mul_f32_e32 v68, v0, v68
	v_mul_f32_e32 v69, v0, v69
	v_mul_f32_e32 v66, v0, v66
	v_mul_f32_e32 v67, v0, v67
	v_mul_f32_e32 v64, v0, v64
	v_mul_f32_e32 v65, v0, v65
	v_mul_f32_e32 v62, v0, v62
	v_mul_f32_e32 v63, v0, v63
	v_mul_f32_e32 v60, v0, v60
	v_mul_f32_e32 v61, v0, v61
	v_mul_f32_e32 v58, v0, v58
	v_mul_f32_e32 v59, v0, v59
	v_mul_f32_e32 v56, v0, v56
	v_mul_f32_e32 v57, v0, v57
	v_mul_f32_e32 v54, v0, v54
	v_mul_f32_e32 v55, v0, v55
	v_mul_f32_e32 v52, v0, v52
	v_mul_f32_e32 v53, v0, v53
	v_mul_f32_e32 v50, v0, v50
	v_mul_f32_e32 v51, v0, v51
	v_mul_f32_e32 v48, v0, v48
	v_mul_f32_e32 v49, v0, v49
	v_mul_f32_e32 v46, v0, v46
	v_mul_f32_e32 v47, v0, v47
	v_mul_f32_e32 v44, v0, v44
	v_mul_f32_e32 v45, v0, v45
	v_mul_f32_e32 v42, v0, v42
	v_mul_f32_e32 v43, v0, v43
	v_mul_f32_e32 v40, v0, v40
	v_mul_f32_e32 v41, v0, v41
	v_mul_f32_e32 v38, v0, v38
	v_mul_f32_e32 v39, v0, v39
	v_mul_f32_e32 v36, v0, v36
	v_mul_f32_e32 v37, v0, v37
	v_mul_f32_e32 v34, v0, v34
	v_mul_f32_e32 v35, v0, v35
	v_mul_f32_e32 v32, v0, v32
	v_mul_f32_e32 v33, v0, v33
	v_mul_f32_e32 v30, v0, v30
	v_mul_f32_e32 v31, v0, v31
	v_mul_f32_e32 v28, v0, v28
	v_mul_f32_e32 v29, v0, v29
	v_mul_f32_e32 v26, v0, v26
	v_mul_f32_e32 v27, v0, v27
	v_mul_f32_e32 v24, v0, v24
	v_mul_f32_e32 v25, v0, v25
	v_mul_f32_e32 v22, v0, v22
	v_mul_f32_e32 v23, v0, v23
	v_mul_f32_e32 v20, v0, v20
	v_mul_f32_e32 v21, v0, v21
	v_mul_f32_e32 v18, v0, v18
	v_mul_f32_e32 v19, v0, v19
	v_mul_f32_e32 v16, v0, v16
	v_mul_f32_e32 v17, v0, v17
.Lattn_noscale_A:
	v_sub_f32_e32 v80, v80, v2
	v_sub_f32_e32 v81, v81, v2
	v_sub_f32_e32 v96, v96, v2
	v_sub_f32_e32 v97, v97, v2
	v_exp_f32_e32 v80, v80
	v_exp_f32_e32 v81, v81
	v_exp_f32_e32 v96, v96
	v_exp_f32_e32 v97, v97
	v_sub_f32_e32 v82, v82, v2
	v_sub_f32_e32 v83, v83, v2
	v_sub_f32_e32 v98, v98, v2
	v_sub_f32_e32 v99, v99, v2
	v_exp_f32_e32 v82, v82
	v_exp_f32_e32 v83, v83
	v_exp_f32_e32 v98, v98
	v_exp_f32_e32 v99, v99
	v_sub_f32_e32 v84, v84, v2
	v_sub_f32_e32 v85, v85, v2
	v_sub_f32_e32 v100, v100, v2
	v_sub_f32_e32 v101, v101, v2
	v_exp_f32_e32 v84, v84
	v_exp_f32_e32 v85, v85
	v_exp_f32_e32 v100, v100
	v_exp_f32_e32 v101, v101
	v_sub_f32_e32 v86, v86, v2
	v_sub_f32_e32 v87, v87, v2
	v_sub_f32_e32 v102, v102, v2
	v_sub_f32_e32 v103, v103, v2
	v_exp_f32_e32 v86, v86
	v_exp_f32_e32 v87, v87
	v_exp_f32_e32 v102, v102
	v_exp_f32_e32 v103, v103
	v_cvt_pk_bf16_f32 v4, v80, v81
	v_cvt_pk_bf16_f32 v5, v82, v83
	v_cvt_pk_bf16_f32 v6, v84, v85
	v_cvt_pk_bf16_f32 v7, v86, v87
	v_cvt_pk_bf16_f32 v8, v96, v97
	v_cvt_pk_bf16_f32 v9, v98, v99
	v_cvt_pk_bf16_f32 v10, v100, v101
	v_cvt_pk_bf16_f32 v11, v102, v103
	v_add_f32_e32 v80, v80, v96
	v_add_f32_e32 v81, v81, v97
	v_add_f32_e32 v82, v82, v98
	v_add_f32_e32 v83, v83, v99
	v_add_f32_e32 v84, v84, v100
	v_add_f32_e32 v85, v85, v101
	v_add_f32_e32 v86, v86, v102
	v_add_f32_e32 v87, v87, v103
	ds_read_b128 v[96:99], v228 offset:32768
	ds_read_b128 v[100:103], v228 offset:36864
	v_mfma_f32_32x32x16_bf16 v[64:79], v[244:247], v[4:7], v[64:79]
	ds_read_b128 v[244:247], v243
	v_sub_f32_e32 v88, v88, v2
	v_sub_f32_e32 v89, v89, v2
	v_sub_f32_e32 v104, v104, v2
	v_sub_f32_e32 v105, v105, v2
	v_exp_f32_e32 v88, v88
	v_exp_f32_e32 v89, v89
	v_exp_f32_e32 v104, v104
	v_exp_f32_e32 v105, v105
	v_mfma_f32_32x32x16_bf16 v[48:63], v[248:251], v[4:7], v[48:63]
	ds_read_b128 v[248:251], v243 offset:4096
	v_sub_f32_e32 v90, v90, v2
	v_sub_f32_e32 v91, v91, v2
	v_sub_f32_e32 v106, v106, v2
	v_sub_f32_e32 v107, v107, v2
	v_exp_f32_e32 v90, v90
	v_exp_f32_e32 v91, v91
	v_exp_f32_e32 v106, v106
	v_exp_f32_e32 v107, v107
	s_waitcnt lgkmcnt(3)
	v_mfma_f32_32x32x16_bf16 v[32:47], v[96:99], v[4:7], v[32:47]
	ds_read_b128 v[96:99], v243 offset:8192
	v_sub_f32_e32 v92, v92, v2
	v_sub_f32_e32 v93, v93, v2
	v_sub_f32_e32 v108, v108, v2
	v_sub_f32_e32 v109, v109, v2
	v_exp_f32_e32 v92, v92
	v_exp_f32_e32 v93, v93
	v_exp_f32_e32 v108, v108
	v_exp_f32_e32 v109, v109
	s_waitcnt lgkmcnt(3)
	v_mfma_f32_32x32x16_bf16 v[16:31], v[100:103], v[4:7], v[16:31]
	ds_read_b128 v[100:103], v243 offset:12288
	v_sub_f32_e32 v94, v94, v2
	v_sub_f32_e32 v95, v95, v2
	v_sub_f32_e32 v110, v110, v2
	v_sub_f32_e32 v111, v111, v2
	v_exp_f32_e32 v94, v94
	v_exp_f32_e32 v95, v95
	v_exp_f32_e32 v110, v110
	v_exp_f32_e32 v111, v111
	v_cvt_pk_bf16_f32 v12, v88, v89
	v_cvt_pk_bf16_f32 v13, v90, v91
	v_cvt_pk_bf16_f32 v14, v92, v93
	v_cvt_pk_bf16_f32 v15, v94, v95
	v_cvt_pk_bf16_f32 v224, v104, v105
	v_cvt_pk_bf16_f32 v225, v106, v107
	v_cvt_pk_bf16_f32 v226, v108, v109
	v_cvt_pk_bf16_f32 v227, v110, v111
	v_add_f32_e32 v88, v88, v104
	v_add_f32_e32 v89, v89, v105
	v_add_f32_e32 v90, v90, v106
	v_add_f32_e32 v91, v91, v107
	v_add_f32_e32 v92, v92, v108
	v_add_f32_e32 v93, v93, v109
	v_add_f32_e32 v94, v94, v110
	v_add_f32_e32 v95, v95, v111
	v_add_f32_e32 v3, 0, v80
	s_waitcnt lgkmcnt(3)
	v_mfma_f32_32x32x16_bf16 v[64:79], v[244:247], v[12:15], v[64:79]
	ds_read_b128 v[244:247], v252
	v_add_f32_e32 v3, v81, v3
	v_add_f32_e32 v3, v82, v3
	s_waitcnt lgkmcnt(3)
	v_mfma_f32_32x32x16_bf16 v[48:63], v[248:251], v[12:15], v[48:63]
	ds_read_b128 v[248:251], v252 offset:4096
	v_add_f32_e32 v3, v83, v3
	v_add_f32_e32 v3, v84, v3
	s_waitcnt lgkmcnt(3)
	v_mfma_f32_32x32x16_bf16 v[32:47], v[96:99], v[12:15], v[32:47]
	ds_read_b128 v[96:99], v252 offset:8192
	v_add_f32_e32 v3, v85, v3
	v_add_f32_e32 v3, v86, v3
	s_waitcnt lgkmcnt(3)
	v_mfma_f32_32x32x16_bf16 v[16:31], v[100:103], v[12:15], v[16:31]
	ds_read_b128 v[100:103], v252 offset:12288
	v_add_f32_e32 v3, v87, v3
	v_add_f32_e32 v3, v88, v3
	s_waitcnt lgkmcnt(3)
	v_mfma_f32_32x32x16_bf16 v[64:79], v[244:247], v[8:11], v[64:79]
	ds_read_b128 v[244:247], v253
	v_add_f32_e32 v3, v89, v3
	s_waitcnt lgkmcnt(3)
	v_mfma_f32_32x32x16_bf16 v[48:63], v[248:251], v[8:11], v[48:63]
	ds_read_b128 v[248:251], v253 offset:4096
	v_add_f32_e32 v3, v90, v3
	s_waitcnt lgkmcnt(3)
	v_mfma_f32_32x32x16_bf16 v[32:47], v[96:99], v[8:11], v[32:47]
	ds_read_b128 v[96:99], v253 offset:8192
	v_add_f32_e32 v3, v91, v3
	s_waitcnt lgkmcnt(3)
	v_mfma_f32_32x32x16_bf16 v[16:31], v[100:103], v[8:11], v[16:31]
	ds_read_b128 v[100:103], v253 offset:12288
	v_add_f32_e32 v3, v92, v3
	s_waitcnt lgkmcnt(3)
	v_mfma_f32_32x32x16_bf16 v[64:79], v[244:247], v[224:227], v[64:79]
	v_add_f32_e32 v3, v93, v3
	s_waitcnt lgkmcnt(2)
	v_mfma_f32_32x32x16_bf16 v[48:63], v[248:251], v[224:227], v[48:63]
	v_add_f32_e32 v3, v94, v3
	s_waitcnt lgkmcnt(1)
	v_mfma_f32_32x32x16_bf16 v[32:47], v[96:99], v[224:227], v[32:47]
	v_add_f32_e32 v3, v95, v3
	s_waitcnt lgkmcnt(0)
	v_mfma_f32_32x32x16_bf16 v[16:31], v[100:103], v[224:227], v[16:31]
	v_fmac_f32_e32 v3, v220, v0
	s_add_i32 s44, s18, 0xa000
	s_cmp_lg_u32 s18, 0x14000
	s_cselect_b32 s18, s44, 0
	s_cmp_eq_u32 s43, s19
	s_cbranch_scc1 .LBB0_603
	v_mov_b32_e32 v221, v2
	v_mov_b32_e32 v220, v3
	s_branch .LBB0_597
.LBB0_603:
	s_waitcnt vmcnt(0)
	v_add_u32_e32 v0, s18, v214
	s_waitcnt lgkmcnt(0)
	s_barrier
	v_add_u32_e32 v8, 0, v0
	ds_read_b128 v[4:7], v8
	s_add_i32 s19, s18, 0
	s_waitcnt lgkmcnt(0)
	v_mfma_f32_32x32x16_bf16 v[80:95], v[4:7], v[156:159], 0
	ds_read_b128 v[4:7], v8 offset:8192
	v_xad_u32 v8, v0, 32, 0
	s_waitcnt lgkmcnt(0)
	v_mfma_f32_32x32x16_bf16 v[96:111], v[4:7], v[156:159], 0
	ds_read_b128 v[4:7], v8
	s_waitcnt lgkmcnt(0)
	v_mfma_f32_32x32x16_bf16 v[80:95], v[4:7], v[152:155], v[80:95]
	ds_read_b128 v[4:7], v8 offset:8192
	v_xad_u32 v8, v0, 64, 0
	s_waitcnt lgkmcnt(0)
	v_mfma_f32_32x32x16_bf16 v[96:111], v[4:7], v[152:155], v[96:111]
	ds_read_b128 v[4:7], v8
	s_waitcnt lgkmcnt(0)
	v_mfma_f32_32x32x16_bf16 v[80:95], v[4:7], v[148:151], v[80:95]
	ds_read_b128 v[4:7], v8 offset:8192
	s_waitcnt lgkmcnt(0)
	v_mfma_f32_32x32x16_bf16 v[96:111], v[4:7], v[148:151], v[96:111]
	v_xor_b32_e32 v4, 0x60, v0
	v_add_u32_e32 v8, 0, v4
	ds_read_b128 v[4:7], v8
	s_waitcnt lgkmcnt(0)
	v_mfma_f32_32x32x16_bf16 v[80:95], v[4:7], v[144:147], v[80:95]
	ds_read_b128 v[4:7], v8 offset:8192
	s_waitcnt lgkmcnt(0)
	v_mfma_f32_32x32x16_bf16 v[96:111], v[4:7], v[144:147], v[96:111]
	v_xor_b32_e32 v4, 0x80, v0
	v_add_u32_e32 v8, 0, v4
	ds_read_b128 v[4:7], v8
	s_waitcnt lgkmcnt(0)
	v_mfma_f32_32x32x16_bf16 v[80:95], v[4:7], v[140:143], v[80:95]
	ds_read_b128 v[4:7], v8 offset:8192
	s_waitcnt lgkmcnt(0)
	v_mfma_f32_32x32x16_bf16 v[96:111], v[4:7], v[140:143], v[96:111]
	v_xor_b32_e32 v4, 0xa0, v0
	v_add_u32_e32 v8, 0, v4
	ds_read_b128 v[4:7], v8
	s_waitcnt lgkmcnt(0)
	v_mfma_f32_32x32x16_bf16 v[80:95], v[4:7], v[136:139], v[80:95]
	ds_read_b128 v[4:7], v8 offset:8192
	s_waitcnt lgkmcnt(0)
	v_mfma_f32_32x32x16_bf16 v[96:111], v[4:7], v[136:139], v[96:111]
	v_xor_b32_e32 v4, 0xc0, v0
	v_add_u32_e32 v8, 0, v4
	ds_read_b128 v[4:7], v8
	v_xor_b32_e32 v0, 0xe0, v0
	v_add_u32_e32 v0, 0, v0
	s_waitcnt lgkmcnt(0)
	v_mfma_f32_32x32x16_bf16 v[80:95], v[4:7], v[132:135], v[80:95]
	ds_read_b128 v[4:7], v8 offset:8192
	s_waitcnt lgkmcnt(0)
	v_mfma_f32_32x32x16_bf16 v[96:111], v[4:7], v[132:135], v[96:111]
	ds_read_b128 v[4:7], v0
	s_waitcnt lgkmcnt(0)
	v_mfma_f32_32x32x16_bf16 v[80:95], v[4:7], v[128:131], v[80:95]
	ds_read_b128 v[4:7], v0 offset:8192
	v_add_u32_e32 v0, s19, v215
	s_waitcnt lgkmcnt(0)
	v_mfma_f32_32x32x16_bf16 v[96:111], v[4:7], v[128:131], v[96:111]
	ds_read_b128 v[4:7], v0 offset:16384
	s_waitcnt lgkmcnt(0)
	v_mfma_f32_32x32x16_bf16 v[80:95], v[4:7], v[124:127], v[80:95]
	ds_read_b128 v[4:7], v0 offset:20480
	v_add_u32_e32 v0, s18, v216
	v_xad_u32 v8, v0, 32, 0
	s_waitcnt lgkmcnt(0)
	v_mfma_f32_32x32x16_bf16 v[96:111], v[4:7], v[124:127], v[96:111]
	ds_read_b128 v[4:7], v8
	s_waitcnt lgkmcnt(0)
	v_mfma_f32_32x32x16_bf16 v[80:95], v[4:7], v[120:123], v[80:95]
	ds_read_b128 v[4:7], v8 offset:4096
	v_xad_u32 v8, v0, 64, 0
	v_xor_b32_e32 v0, 0x60, v0
	v_add_u32_e32 v0, 0, v0
	s_waitcnt lgkmcnt(0)
	v_mfma_f32_32x32x16_bf16 v[96:111], v[4:7], v[120:123], v[96:111]
	ds_read_b128 v[4:7], v8
	s_waitcnt lgkmcnt(0)
	v_mfma_f32_32x32x16_bf16 v[80:95], v[4:7], v[116:119], v[80:95]
	ds_read_b128 v[4:7], v0
	s_waitcnt lgkmcnt(0)
	v_mfma_f32_32x32x16_bf16 v[80:95], v[4:7], v[112:115], v[80:95]
	ds_read_b128 v[4:7], v8 offset:4096
	ds_read_b128 v[8:11], v0 offset:4096
	s_waitcnt lgkmcnt(0)
	v_mfma_f32_32x32x16_bf16 v[96:111], v[4:7], v[116:119], v[96:111]
	s_nop 7
	v_max_f32_e32 v0, v81, v81
	v_max_f32_e32 v12, v80, v80
	v_max_f32_e32 v0, v12, v0
	v_max3_f32 v0, v0, v82, v83
	v_max3_f32 v0, v0, v84, v85
	v_max3_f32 v0, v0, v86, v87
	v_max3_f32 v0, v0, v88, v89
	v_mfma_f32_32x32x16_bf16 v[96:111], v[8:11], v[112:115], v[96:111]
	v_max3_f32 v0, v0, v90, v91
	v_max3_f32 v0, v0, v92, v93
	v_max3_f32 v0, v0, v94, v95
	s_nop 8
	v_max3_f32 v0, v0, v96, v97
	v_max3_f32 v0, v0, v98, v99
	v_max3_f32 v0, v0, v100, v101
	v_max3_f32 v0, v0, v102, v103
	v_max3_f32 v0, v0, v104, v105
	v_max3_f32 v0, v0, v106, v107
	v_max3_f32 v0, v0, v108, v109
	v_max3_f32 v0, v0, v110, v111
	ds_bpermute_b32 v4, v219, v0
	s_waitcnt lgkmcnt(0)
	v_max3_f32 v4, v2, v0, v4
	v_sub_f32_e32 v0, v2, v4
	v_exp_f32_e32 v0, v0
	v_cmp_gt_f32_e32 vcc, v4, v2
	s_cbranch_vccz .LBB0_591
	v_mul_f32_e32 v78, v0, v78
	v_mul_f32_e32 v79, v0, v79
	v_mul_f32_e32 v76, v0, v76
	v_mul_f32_e32 v77, v0, v77
	v_mul_f32_e32 v74, v0, v74
	v_mul_f32_e32 v75, v0, v75
	v_mul_f32_e32 v72, v0, v72
	v_mul_f32_e32 v73, v0, v73
	v_mul_f32_e32 v70, v0, v70
	v_mul_f32_e32 v71, v0, v71
	v_mul_f32_e32 v68, v0, v68
	v_mul_f32_e32 v69, v0, v69
	v_mul_f32_e32 v66, v0, v66
	v_mul_f32_e32 v67, v0, v67
	v_mul_f32_e32 v64, v0, v64
	v_mul_f32_e32 v65, v0, v65
	v_mul_f32_e32 v62, v0, v62
	v_mul_f32_e32 v63, v0, v63
	v_mul_f32_e32 v60, v0, v60
	v_mul_f32_e32 v61, v0, v61
	v_mul_f32_e32 v58, v0, v58
	v_mul_f32_e32 v59, v0, v59
	v_mul_f32_e32 v56, v0, v56
	v_mul_f32_e32 v57, v0, v57
	v_mul_f32_e32 v54, v0, v54
	v_mul_f32_e32 v55, v0, v55
	v_mul_f32_e32 v52, v0, v52
	v_mul_f32_e32 v53, v0, v53
	v_mul_f32_e32 v50, v0, v50
	v_mul_f32_e32 v51, v0, v51
	v_mul_f32_e32 v48, v0, v48
	v_mul_f32_e32 v49, v0, v49
	v_mul_f32_e32 v46, v0, v46
	v_mul_f32_e32 v47, v0, v47
	v_mul_f32_e32 v44, v0, v44
	v_mul_f32_e32 v45, v0, v45
	v_mul_f32_e32 v42, v0, v42
	v_mul_f32_e32 v43, v0, v43
	v_mul_f32_e32 v40, v0, v40
	v_mul_f32_e32 v41, v0, v41
	v_mul_f32_e32 v38, v0, v38
	v_mul_f32_e32 v39, v0, v39
	v_mul_f32_e32 v36, v0, v36
	v_mul_f32_e32 v37, v0, v37
	v_mul_f32_e32 v34, v0, v34
	v_mul_f32_e32 v35, v0, v35
	v_mul_f32_e32 v32, v0, v32
	v_mul_f32_e32 v33, v0, v33
	v_mul_f32_e32 v30, v0, v30
	v_mul_f32_e32 v31, v0, v31
	v_mul_f32_e32 v28, v0, v28
	v_mul_f32_e32 v29, v0, v29
	v_mul_f32_e32 v26, v0, v26
	v_mul_f32_e32 v27, v0, v27
	v_mul_f32_e32 v24, v0, v24
	v_mul_f32_e32 v25, v0, v25
	v_mul_f32_e32 v22, v0, v22
	v_mul_f32_e32 v23, v0, v23
	v_mul_f32_e32 v20, v0, v20
	v_mul_f32_e32 v21, v0, v21
	v_mul_f32_e32 v18, v0, v18
	v_mul_f32_e32 v19, v0, v19
	v_mul_f32_e32 v16, v0, v16
	v_mul_f32_e32 v17, v0, v17
	s_branch .LBB0_591
